# MLA softmax: while every score in the wave tile stays within +-64 (log2 units) the running max is pinned at 0, so exp2 takes the scores directly (no subtract), and one 64-value max tree replaces the t
# speedup vs baseline: 1.0144x; 1.0116x over previous
; __device__ __forceinline__ int hw_lane_id() { return (int)__builtin_amdgcn_mbcnt_hi(~0u, __builtin_amdgcn_mbcnt_lo(~0u, 0u)); }
; #define LAS __attribute__((address_space(3)))
; __device__ __forceinline__ void mla_unit2(LAS unsigned char* lds, const bf16_t* QB, const bf16_t* KB, const bf16_t* VT, bf16_t* OB, int b, int h, int qb, int wv) {
;     int tid_ = wv * 64 + hw_lane_id(); asm volatile("" : "+v"(tid_));
;     const int tid = tid_, lane = tid & 63, wid = __builtin_amdgcn_readfirstlane(tid >> 6), r = lane & 31, hh = lane >> 5;
;     const int q0 = qb * 512 + wid * 64;
;     const size_t rowbase = (size_t)b * SEQ;
;     bf16x8 qa[6], qbf[6];
;     { const bf16_t* qp = QB + (rowbase + q0 + r) * NQB + h * 96 + 8 * hh;
; #pragma unroll
;       for (int s = 0; s < 6; ++s) { qa[s] = *(const bf16x8*)(qp + 16 * s); qbf[s] = *(const bf16x8*)(qp + (size_t)32 * NQB + 16 * s); } }
;     f32x16 oa0, oa1, ob0, ob1;
; #pragma unroll
;     for (int i = 0; i < 16; ++i) { oa0[i] = 0.f; oa1[i] = 0.f; ob0[i] = 0.f; ob1[i] = 0.f; }
;     float ma = -INFINITY, mb = -INFINITY, la = 0.f, lb = 0.f;
;     const int ntiles = 8 * (qb + 1), nact = q0 / 64 + 1, tl = ntiles - 1;
;     const int kA_key = tid / 12, kA_part = tid % 12, kC_key = (512 + (tid & 255)) / 12, kC_part = (512 + (tid & 255)) % 12, v_d = tid >> 3, v_part = tid & 7;
;     const bf16_t* gKA = KB + (rowbase + kA_key) * NQB + h * 96 + kA_part * 8;
;     const bf16_t* gKC = KB + (rowbase + kC_key) * NQB + h * 96 + kC_part * 8;
;     const bf16_t* gV = VT + ((size_t)(b * 8 + h) * 64 + v_d) * SEQ + v_part * 8;
;     const int lKA = kA_key * MK_ROW + kA_part * 16, lKC = kC_key * MK_ROW + kC_part * 16, lV = MK_BYTES + v_d * MV_ROW + v_part * 16;
;     u32x4 ra = *(const u32x4*)gKA, rc = *(const u32x4*)gKC, rv = *(const u32x4*)gV;
;     __syncthreads();
;     *(LAS u32x4*)(lds + lKA) = ra; *(LAS u32x4*)(lds + lKC) = rc; *(LAS u32x4*)(lds + lV) = rv;
;     __syncthreads();
.LBB0_660:
	v_mov_b32_e32 v20, v194
	s_mov_b32 s12, 0x2aaaaaab
	s_xor_b64 s[30:31], s[0:1], -1
	v_mul_hi_i32 v0, v20, s12
	v_lshrrev_b32_e32 v2, 31, v0
	v_ashrrev_i32_e32 v0, 1, v0
	v_add_u32_e32 v14, v0, v2
	v_mul_lo_u32 v0, v14, 12
	v_sub_u32_e32 v24, v20, v0
	v_mov_b32_e32 v0, 0xff
	s_movk_i32 s12, 0x200
	v_bitop3_b16 v0, v20, s12, v0 bitop3:0xec
	s_mov_b32 s12, 0xaaab
	v_mul_u32_u24_sdwa v2, v0, s12 dst_sel:DWORD dst_unused:UNUSED_PAD src0_sel:WORD_0 src1_sel:DWORD
	v_lshrrev_b32_e32 v25, 19, v2
	v_mul_lo_u16_e32 v2, 12, v25
	v_ashrrev_i32_e32 v15, 31, v14
	v_sub_u16_e32 v0, v0, v2
	v_lshl_add_u64 v[2:3], s[4:5], 0, v[14:15]
	v_mov_b64_e32 v[4:5], s[8:9]
	s_and_b64 s[0:1], s[0:1], exec
	v_mad_u64_u32 v[6:7], s[16:17], v2, s33, v[4:5]
	v_lshlrev_b32_e32 v2, 3, v24
	s_cselect_b32 s12, s69, s68
	v_readfirstlane_b32 s0, v20
	v_mad_i32_i24 v7, v3, s33, v7
	v_ashrrev_i32_e32 v3, 31, v2
	s_lshl_b32 s75, s12, 9
	s_and_b32 s70, s0, 0xffffffc0
	v_lshl_add_u64 v[200:201], v[2:3], 1, v[6:7]
	v_or_b32_e32 v2, s4, v25
	s_add_i32 s70, s70, s75
	v_ashrrev_i32_e32 v16, 3, v20
	v_mad_u64_u32 v[2:3], s[16:17], v2, s33, v[4:5]
	v_mov_b32_e32 v22, 0x600
	s_ashr_i32 s0, s70, 31
	v_mad_i32_i24 v3, s5, v22, v3
	v_lshlrev_b32_e32 v0, 4, v0
	v_ashrrev_i32_e32 v17, 31, v16
	v_and_b32_e32 v15, 31, v20
	s_add_u32 s1, s4, s70
	v_lshl_add_u64 v[202:203], v[2:3], 0, v[0:1]
	v_lshlrev_b64 v[2:3], 14, v[16:17]
	v_lshlrev_b32_e32 v12, 4, v20
	v_bfe_u32 v17, v20, 5, 1
	v_or_b32_e32 v198, s1, v15
	v_mov_b64_e32 v[20:21], s[6:7]
	s_addc_u32 s16, s5, s0
	v_mad_u64_u32 v[20:21], s[0:1], v198, s33, v[20:21]
	v_mad_i32_i24 v21, s16, v22, v21
	v_lshlrev_b32_e32 v206, 4, v17
	v_mov_b32_e32 v207, v1
	v_lshl_add_u64 v[10:11], s[10:11], 0, v[2:3]
	v_and_b32_e32 v18, 0x70, v12
	v_mov_b32_e32 v19, v1
	v_lshl_add_u64 v[20:21], v[20:21], 0, v[206:207]
	s_mov_b32 s0, 0xc000
	v_lshl_add_u64 v[204:205], v[10:11], 0, v[18:19]
	v_add_co_u32_e32 v22, vcc, s0, v20
	global_load_dwordx4 v[2:5], v[200:201], off
	global_load_dwordx4 v[6:9], v[202:203], off
	global_load_dwordx4 v[10:13], v[204:205], off
	global_load_dwordx4 v[144:147], v[20:21], off
	v_addc_co_u32_e32 v23, vcc, 0, v21, vcc
	global_load_dwordx4 v[148:151], v[20:21], off offset:32
	global_load_dwordx4 v[152:155], v[20:21], off offset:64
	global_load_dwordx4 v[156:159], v[22:23], off offset:32
	global_load_dwordx4 v[160:163], v[22:23], off offset:64
	global_load_dwordx4 v[164:167], v[20:21], off offset:96
	global_load_dwordx4 v[168:171], v[20:21], off offset:128
	global_load_dwordx4 v[172:175], v[22:23], off offset:96
	global_load_dwordx4 v[176:179], v[22:23], off offset:128
	global_load_dwordx4 v[180:183], v[22:23], off
	global_load_dwordx4 v[184:187], v[20:21], off offset:160
	global_load_dwordx4 v[188:191], v[22:23], off offset:160
	s_movk_i32 s0, 0xd0
	v_mul_lo_u32 v14, v14, s0
	v_mul_lo_u16_e32 v19, 0xd0, v25
	s_lshl_b32 s0, s12, 3
	v_lshl_add_u32 v197, v24, 4, v14
	v_add_u32_e32 v207, v0, v19
	s_or_b32 s73, s0, 7
	v_add_u32_e32 v0, 0, v197
	v_add_u32_e32 v14, 0, v207
	v_mad_u64_u32 v[208:209], s[0:1], v16, s19, v[18:19]
	s_or_b32 s74, s70, 32
	s_waitcnt vmcnt(63) expcnt(7) lgkmcnt(15)
	s_barrier
	v_mul_u32_u24_e32 v209, 0xd0, v15
	v_or_b32_e32 v211, s70, v15
	v_mul_u32_u24_e32 v213, 0x90, v15
	v_or_b32_e32 v214, s74, v15
	v_mov_b32_e32 v15, v1
	v_lshlrev_b32_e32 v196, 3, v17
	v_lshlrev_b32_e32 v212, 2, v17
	s_mov_b32 s71, 0
	s_mov_b32 s100, 1
	s_ashr_i32 s72, s70, 6
	v_mov_b32_e32 v199, s16
	s_addk_i32 s75, 0x200
	v_mov_b32_e32 v223, 0
	s_waitcnt vmcnt(14)
	ds_write_b128 v0, v[2:5]
	s_waitcnt vmcnt(13)
	ds_write_b128 v14, v[6:9]
	v_add_u32_e32 v0, 0, v208
	v_mov_b32_e32 v14, v1
	s_waitcnt vmcnt(12)
	ds_write_b128 v0, v[10:13] offset:13312
	v_mov_b32_e32 v0, v1
	v_mov_b32_e32 v2, v1
	v_mov_b32_e32 v3, v1
	v_mov_b32_e32 v4, v1
	v_mov_b32_e32 v5, v1
	v_mov_b32_e32 v6, v1
	v_mov_b32_e32 v7, v1
	v_mov_b32_e32 v8, v1
	v_mov_b32_e32 v9, v1
	v_mov_b32_e32 v10, v1
	v_mov_b32_e32 v11, v1
	v_mov_b32_e32 v12, v1
	v_mov_b32_e32 v13, v1
	v_mov_b64_e32 v[30:31], v[14:15]
	v_mov_b64_e32 v[46:47], v[14:15]
	v_mov_b64_e32 v[62:63], v[14:15]
	v_mov_b64_e32 v[78:79], v[14:15]
	v_mov_b32_e32 v222, 0
	s_mov_b32 s0, 0
	v_mov_b32_e32 v225, 0
	v_mov_b32_e32 v224, 0
	v_mov_b64_e32 v[28:29], v[12:13]
	v_mov_b64_e32 v[26:27], v[10:11]
	v_mov_b64_e32 v[24:25], v[8:9]
	v_mov_b64_e32 v[22:23], v[6:7]
	v_mov_b64_e32 v[20:21], v[4:5]
	v_mov_b64_e32 v[18:19], v[2:3]
	v_mov_b64_e32 v[16:17], v[0:1]
	v_mov_b64_e32 v[44:45], v[12:13]
	v_mov_b64_e32 v[42:43], v[10:11]
	v_mov_b64_e32 v[40:41], v[8:9]
	v_mov_b64_e32 v[38:39], v[6:7]
	v_mov_b64_e32 v[36:37], v[4:5]
	v_mov_b64_e32 v[34:35], v[2:3]
	v_mov_b64_e32 v[32:33], v[0:1]
	v_mov_b64_e32 v[60:61], v[12:13]
	v_mov_b64_e32 v[58:59], v[10:11]
	v_mov_b64_e32 v[56:57], v[8:9]
	v_mov_b64_e32 v[54:55], v[6:7]
	v_mov_b64_e32 v[52:53], v[4:5]
	v_mov_b64_e32 v[50:51], v[2:3]
	v_mov_b64_e32 v[48:49], v[0:1]
	v_mov_b64_e32 v[76:77], v[12:13]
	v_mov_b64_e32 v[74:75], v[10:11]
	v_mov_b64_e32 v[72:73], v[8:9]
	v_mov_b64_e32 v[70:71], v[6:7]
	v_mov_b64_e32 v[68:69], v[4:5]
	v_mov_b64_e32 v[66:67], v[2:3]
	v_mov_b64_e32 v[64:65], v[0:1]
	s_waitcnt lgkmcnt(0)
	s_barrier
; #define LAS __attribute__((address_space(3)))
; #define MFMA32(a, b, c) __builtin_amdgcn_mfma_f32_32x32x16_bf16((a), (b), (c), 0, 0, 0)
; __device__ __forceinline__ int crow(int i, int hh) { return (i & 3) + 8 * (i >> 2) + 4 * hh; }
; __device__ __forceinline__ void mla_softmax(f32x16& s0, f32x16& s1, f32x16& o0, f32x16& o1, float& m, float& l, int k0, int qrow0, int r, int hh) {
;     if (k0 + 63 > qrow0) {
;         const int qpos = qrow0 + r;
; #pragma unroll
;         for (int i = 0; i < 16; ++i) { const int kp = k0 + crow(i, hh); if (kp > qpos) s0[i] = -INFINITY; if (kp + 32 > qpos) s1[i] = -INFINITY; }
;     }
; __device__ __forceinline__ void mla_unit2(LAS unsigned char* lds, const bf16_t* QB, const bf16_t* KB, const bf16_t* VT, bf16_t* OB, int b, int h, int qb, int wv) {
;     ...
;     for (int t = 0; t < ntiles; ++t) {
;         LAS unsigned char* cur = lds + (t & 1) * M2BUF;
;         { const int tn = (t + 1 < tl) ? t + 1 : tl;
;           ra = *(const u32x4*)(gKA + (size_t)tn * 64 * NQB); rc = *(const u32x4*)(gKC + (size_t)tn * 64 * NQB); rv = *(const u32x4*)(gV + tn * 64); }
;         if (t < nact) {
;             const int k0 = t * 64;
;             f32x16 sa0, sa1, sb0, sb1;
;             { const LAS unsigned char* kp = cur + r * MK_ROW + hh * 16;
; #pragma unroll
;               for (int i = 0; i < 16; ++i) { sa0[i] = 0.f; sa1[i] = 0.f; sb0[i] = 0.f; sb1[i] = 0.f; }
; #pragma unroll
;               for (int hf = 0; hf < 2; ++hf) {
;                   bf16x8 ka[3], kc[3];
; #pragma unroll
;                   for (int s = 0; s < 3; ++s) { ka[s] = *(const LAS bf16x8*)(kp + (3 * hf + s) * 32); kc[s] = *(const LAS bf16x8*)(kp + 32 * MK_ROW + (3 * hf + s) * 32); }
;                   __builtin_amdgcn_sched_barrier(0);
; #pragma unroll
;                   for (int s = 0; s < 3; ++s) { sa0 = MFMA32(ka[s], qa[3 * hf + s], sa0); sa1 = MFMA32(kc[s], qa[3 * hf + s], sa1); sb0 = MFMA32(ka[s], qbf[3 * hf + s], sb0); sb1 = MFMA32(kc[s], qbf[3 * hf + s], sb1); }
;                   __builtin_amdgcn_sched_barrier(0);
;               } }
.LBB0_661:
	s_add_i32 s76, s0, 1
	s_min_u32 s1, s76, s73
	s_mul_i32 s12, s1, 0x18000
	v_lshl_add_u64 v[2:3], v[200:201], 0, s[12:13]
	v_lshl_add_u64 v[4:5], v[202:203], 0, s[12:13]
	s_lshl_b32 s12, s1, 7
	v_lshl_add_u64 v[10:11], v[204:205], 0, s[12:13]
	global_load_dwordx4 v[6:9], v[2:3], off
	s_nop 0
	global_load_dwordx4 v[2:5], v[4:5], off
	s_cmp_gt_i32 s0, s72
	global_load_dwordx4 v[10:13], v[10:11], off
	s_cbranch_scc1 .LBB0_676
	s_bitcmp1_b32 s0, 0
	s_cselect_b32 s0, 0x5800, 0
	s_add_i32 s12, s0, 0
	v_add3_u32 v0, s12, v209, v206
	ds_read_b128 v[80:83], v0
	ds_read_b128 v[226:229], v0 offset:32
	ds_read_b128 v[84:87], v0 offset:6656
	ds_read_b128 v[230:233], v0 offset:64
	ds_read_b128 v[234:237], v0 offset:6688
	ds_read_b128 v[238:241], v0 offset:6720
	s_waitcnt vmcnt(14) lgkmcnt(5)
	v_mfma_f32_32x32x16_bf16 v[128:143], v[80:83], v[144:147], 0
	s_waitcnt lgkmcnt(3)
	v_mfma_f32_32x32x16_bf16 v[112:127], v[84:87], v[144:147], 0
	s_waitcnt vmcnt(5)
	v_mfma_f32_32x32x16_bf16 v[96:111], v[80:83], v[180:183], 0
	v_mfma_f32_32x32x16_bf16 v[80:95], v[84:87], v[180:183], 0
	v_mfma_f32_32x32x16_bf16 v[128:143], v[226:229], v[148:151], v[128:143]
	s_waitcnt lgkmcnt(1)
	v_mfma_f32_32x32x16_bf16 v[112:127], v[234:237], v[148:151], v[112:127]
	v_mfma_f32_32x32x16_bf16 v[96:111], v[226:229], v[156:159], v[96:111]
	v_mfma_f32_32x32x16_bf16 v[80:95], v[234:237], v[156:159], v[80:95]
	v_mfma_f32_32x32x16_bf16 v[128:143], v[230:233], v[152:155], v[128:143]
	s_waitcnt lgkmcnt(0)
	v_mfma_f32_32x32x16_bf16 v[112:127], v[238:241], v[152:155], v[112:127]
	v_mfma_f32_32x32x16_bf16 v[96:111], v[230:233], v[160:163], v[96:111]
	v_mfma_f32_32x32x16_bf16 v[80:95], v[238:241], v[160:163], v[80:95]
	ds_read_b128 v[226:229], v0 offset:96
	ds_read_b128 v[230:233], v0 offset:128
	ds_read_b128 v[234:237], v0 offset:6752
	ds_read_b128 v[238:241], v0 offset:160
	ds_read_b128 v[242:245], v0 offset:6784
	ds_read_b128 v[246:249], v0 offset:6816
	s_waitcnt lgkmcnt(5)
	v_mfma_f32_32x32x16_bf16 v[128:143], v[226:229], v[164:167], v[128:143]
	s_waitcnt lgkmcnt(3)
	v_mfma_f32_32x32x16_bf16 v[112:127], v[234:237], v[164:167], v[112:127]
	v_mfma_f32_32x32x16_bf16 v[96:111], v[226:229], v[172:175], v[96:111]
	v_mfma_f32_32x32x16_bf16 v[80:95], v[234:237], v[172:175], v[80:95]
	v_mfma_f32_32x32x16_bf16 v[128:143], v[230:233], v[168:171], v[128:143]
	s_waitcnt lgkmcnt(1)
	v_mfma_f32_32x32x16_bf16 v[112:127], v[242:245], v[168:171], v[112:127]
	v_mfma_f32_32x32x16_bf16 v[96:111], v[230:233], v[176:179], v[96:111]
	v_mfma_f32_32x32x16_bf16 v[80:95], v[242:245], v[176:179], v[80:95]
	s_waitcnt vmcnt(4)
	v_mfma_f32_32x32x16_bf16 v[128:143], v[238:241], v[184:187], v[128:143]
	s_waitcnt lgkmcnt(0)
	v_mfma_f32_32x32x16_bf16 v[112:127], v[246:249], v[184:187], v[112:127]
	s_waitcnt vmcnt(3)
	v_mfma_f32_32x32x16_bf16 v[96:111], v[238:241], v[188:191], v[96:111]
	v_mfma_f32_32x32x16_bf16 v[80:95], v[246:249], v[188:191], v[80:95]
	s_add_i32 s25, s71, 63
	s_cmp_le_i32 s25, s70
	s_nop 7
	s_cbranch_scc1 .Lmla_nomask
	s_cmp_eq_u32 s100, 0
	s_cbranch_scc1 .Lmla_m663
	s_mov_b32 s100, 0
	s_cmp_lg_u32 s71, 0
	s_cbranch_scc1 .Lmla_m663
	v_mov_b32_e32 v224, 0xff800000
	v_mov_b32_e32 v223, 0xff800000
.Lmla_m663:
	v_add_u32_e32 v249, s71, v212
	v_add_u32_e32 v192, 32, v249
	v_add_u32_e32 v219, 33, v249
	v_add_u32_e32 v250, 2, v249
	v_add_u32_e32 v251, 34, v249
	v_add_u32_e32 v247, 3, v249
	v_add_u32_e32 v248, 35, v249
	v_add_u32_e32 v245, 8, v249
	v_add_u32_e32 v246, 40, v249
	v_add_u32_e32 v243, 9, v249
	v_add_u32_e32 v244, 41, v249
	v_add_u32_e32 v241, 10, v249
	v_add_u32_e32 v242, 42, v249
	v_add_u32_e32 v239, 11, v249
	v_add_u32_e32 v240, 43, v249
	v_add_u32_e32 v237, 16, v249
	v_add_u32_e32 v238, 48, v249
	v_add_u32_e32 v235, 17, v249
	v_add_u32_e32 v236, 49, v249
	v_add_u32_e32 v233, 18, v249
	v_add_u32_e32 v234, 50, v249
	v_add_u32_e32 v231, 19, v249
	v_add_u32_e32 v232, 51, v249
	v_add_u32_e32 v229, 24, v249
	v_add_u32_e32 v230, 56, v249
	v_add_u32_e32 v227, 25, v249
	v_add_u32_e32 v228, 57, v249
	v_add_u32_e32 v210, 26, v249
	v_add_u32_e32 v226, 58, v249
	v_add_u32_e32 v0, 27, v249
	v_add_u32_e32 v15, 59, v249
	v_cmp_le_i32_e64 s[0:1], v192, v211
	v_cmp_le_i32_e64 s[36:37], v219, v211
	v_cmp_le_i32_e64 s[38:39], v251, v211
	v_cmp_le_i32_e64 s[40:41], v248, v211
	v_cmp_le_i32_e64 s[42:43], v246, v211
	v_cmp_le_i32_e64 s[44:45], v244, v211
	v_cmp_le_i32_e64 s[46:47], v242, v211
	v_cmp_le_i32_e64 s[48:49], v240, v211
	v_cmp_le_i32_e64 s[50:51], v238, v211
	v_cmp_le_i32_e64 s[52:53], v236, v211
	v_cmp_le_i32_e64 s[54:55], v234, v211
	v_cmp_le_i32_e64 s[56:57], v232, v211
	v_cmp_le_i32_e64 s[58:59], v230, v211
	v_cmp_le_i32_e64 s[60:61], v228, v211
	v_cmp_le_i32_e64 s[62:63], v226, v211
	v_cmp_le_i32_e32 vcc, v249, v211
	v_cndmask_b32_e64 v112, v221, v112, s[0:1]
	v_cmp_lt_i32_e64 s[0:1], v249, v211
	v_cndmask_b32_e64 v113, v221, v113, s[36:37]
	v_cmp_le_i32_e64 s[36:37], v250, v211
	v_cndmask_b32_e64 v114, v221, v114, s[38:39]
	v_cmp_le_i32_e64 s[38:39], v247, v211
	v_cndmask_b32_e64 v115, v221, v115, s[40:41]
	v_cmp_le_i32_e64 s[40:41], v245, v211
	v_cndmask_b32_e64 v116, v221, v116, s[42:43]
	v_cmp_le_i32_e64 s[42:43], v243, v211
	v_cndmask_b32_e64 v117, v221, v117, s[44:45]
	v_cmp_le_i32_e64 s[44:45], v241, v211
	v_cndmask_b32_e64 v118, v221, v118, s[46:47]
	v_cmp_le_i32_e64 s[46:47], v239, v211
	v_cndmask_b32_e64 v119, v221, v119, s[48:49]
	v_cmp_le_i32_e64 s[48:49], v237, v211
	v_cndmask_b32_e64 v120, v221, v120, s[50:51]
	v_cmp_le_i32_e64 s[50:51], v235, v211
	v_cndmask_b32_e64 v121, v221, v121, s[52:53]
	v_cmp_le_i32_e64 s[52:53], v233, v211
	v_cndmask_b32_e64 v122, v221, v122, s[54:55]
	v_cmp_le_i32_e64 s[54:55], v231, v211
	v_cndmask_b32_e64 v123, v221, v123, s[56:57]
	v_cmp_le_i32_e64 s[56:57], v229, v211
	v_cndmask_b32_e64 v124, v221, v124, s[58:59]
	v_cmp_le_i32_e64 s[58:59], v227, v211
	v_cndmask_b32_e64 v125, v221, v125, s[60:61]
	v_cmp_le_i32_e64 s[60:61], v210, v211
	v_cndmask_b32_e64 v126, v221, v126, s[62:63]
	v_cmp_le_i32_e64 s[62:63], v0, v211
	v_cmp_gt_i32_e64 s[64:65], v15, v211
	s_and_saveexec_b64 s[16:17], s[64:65]
	v_mov_b32_e32 v127, s2
	s_or_b64 exec, exec, s[16:17]
	v_cndmask_b32_e64 v129, v221, v129, s[0:1]
	v_cndmask_b32_e32 v128, v221, v128, vcc
	v_cndmask_b32_e64 v130, v221, v130, s[36:37]
	v_cndmask_b32_e64 v131, v221, v131, s[38:39]
	v_cndmask_b32_e64 v132, v221, v132, s[40:41]
	v_cndmask_b32_e64 v133, v221, v133, s[42:43]
	v_cndmask_b32_e64 v134, v221, v134, s[44:45]
	v_cndmask_b32_e64 v135, v221, v135, s[46:47]
	v_cndmask_b32_e64 v136, v221, v136, s[48:49]
	v_cndmask_b32_e64 v137, v221, v137, s[50:51]
	v_cndmask_b32_e64 v138, v221, v138, s[52:53]
	v_cndmask_b32_e64 v139, v221, v139, s[54:55]
	v_cndmask_b32_e64 v140, v221, v140, s[56:57]
	v_cndmask_b32_e64 v141, v221, v141, s[58:59]
	v_cndmask_b32_e64 v142, v221, v142, s[60:61]
	v_cndmask_b32_e64 v143, v221, v143, s[62:63]

; __device__ __forceinline__ float xhalf_max(float x) { float a, b; xhalf_swap(x, a, b); float m; asm("v_max3_f32 %0, %1, %2, %3" : "=v"(m) : "v"(x), "v"(a), "v"(b)); return m; }
; __device__ __forceinline__ float max3f(float a, float b, float c) { float r; asm("v_max3_f32 %0, %1, %2, %3" : "=v"(r) : "v"(a), "v"(b), "v"(c)); return r; }
; __device__ __forceinline__ void mla_softmax(f32x16& s0, f32x16& s1, f32x16& o0, f32x16& o1, float& m, float& l, int k0, int qrow0, int r, int hh) {
;     ...
;     const float a16 = max16(s0), b16 = max16(s1);
;     const float mx = xhalf_max(max3f(a16, b16, b16));
;     float alpha = 1.0f;
;     if (__any(mx > m + RESCALE_THR)) {
;         const float mn = fmaxf(m, mx); alpha = __builtin_amdgcn_exp2f(m - mn); m = mn;
; #pragma unroll
;         for (int i = 0; i < 16; ++i) { o0[i] *= alpha; o1[i] *= alpha; }
;     }
.Lmla_nomask:
	s_cmp_lg_u32 s100, 0
	s_cbranch_scc0 .LBB0_666
.Lmla_fastq:
	v_max3_f32 v226, v128, v129, v130
	v_max3_f32 v227, v131, v132, v133
	v_max3_f32 v228, v134, v135, v136
	v_max3_f32 v229, v137, v138, v139
	v_max3_f32 v230, v140, v141, v142
	v_max3_f32 v231, v143, v112, v113
	v_max3_f32 v232, v114, v115, v116
	v_max3_f32 v233, v117, v118, v119
	v_max3_f32 v234, v120, v121, v122
	v_max3_f32 v235, v123, v124, v125
	v_max3_f32 v236, v126, v127, v96
	v_max3_f32 v237, v97, v98, v99
	v_max3_f32 v238, v100, v101, v102
	v_max3_f32 v239, v103, v104, v105
	v_max3_f32 v240, v106, v107, v108
	v_max3_f32 v241, v109, v110, v111
	v_max3_f32 v242, v80, v81, v82
	v_max3_f32 v243, v83, v84, v85
	v_max3_f32 v244, v86, v87, v88
	v_max3_f32 v245, v89, v90, v91
	v_max3_f32 v246, v92, v93, v94
	v_max3_f32 v247, v226, v227, v228
	v_max3_f32 v248, v229, v230, v231
	v_max3_f32 v249, v232, v233, v234
	v_max3_f32 v250, v235, v236, v237
	v_max3_f32 v251, v238, v239, v240
	v_max3_f32 v192, v241, v242, v243
	v_max3_f32 v193, v244, v245, v246
	v_max3_f32 v194, v247, v248, v249
	v_max3_f32 v195, v250, v251, v192
	v_max3_f32 v215, v194, v195, v193
	v_max_f32_e32 v14, v215, v95
	s_cmp_lg_u32 s71, 0
	s_cbranch_scc1 .Lmla_fq_chk
	v_min3_f32 v226, v128, v129, v130
	v_min3_f32 v227, v131, v132, v133
	v_min3_f32 v228, v134, v135, v136
	v_min3_f32 v229, v137, v138, v139
	v_min3_f32 v230, v140, v141, v142
	v_min3_f32 v231, v143, v112, v113
	v_min3_f32 v232, v114, v115, v116
	v_min3_f32 v233, v117, v118, v119
	v_min3_f32 v234, v120, v121, v122
	v_min3_f32 v235, v123, v124, v125
	v_min3_f32 v236, v126, v127, v96
	v_min3_f32 v237, v97, v98, v99
	v_min3_f32 v238, v100, v101, v102
	v_min3_f32 v239, v103, v104, v105
	v_min3_f32 v240, v106, v107, v108
	v_min3_f32 v241, v109, v110, v111
	v_min3_f32 v242, v80, v81, v82
	v_min3_f32 v243, v83, v84, v85
	v_min3_f32 v244, v86, v87, v88
	v_min3_f32 v245, v89, v90, v91
	v_min3_f32 v246, v92, v93, v94
	v_min3_f32 v247, v226, v227, v228
	v_min3_f32 v248, v229, v230, v231
	v_min3_f32 v249, v232, v233, v234
	v_min3_f32 v250, v235, v236, v237
	v_min3_f32 v251, v238, v239, v240
	v_min3_f32 v192, v241, v242, v243
	v_min3_f32 v193, v244, v245, v246
	v_min3_f32 v194, v247, v248, v249
	v_min3_f32 v195, v250, v251, v192
	v_min3_f32 v215, v194, v195, v193
	v_min_f32_e32 v0, v215, v95
	v_cmp_gt_f32_e32 vcc, 0xc2800000, v0
	s_cbranch_vccnz .Lmla_fq_trip
.Lmla_fq_chk:
	v_cmp_lt_f32_e32 vcc, 0x42800000, v14
	s_cbranch_vccz .Lmla_fastS
.Lmla_fq_trip:
	s_mov_b32 s100, 0
	s_cmp_lg_u32 s71, 0
	s_cbranch_scc1 .LBB0_666
	v_mov_b32_e32 v224, 0xff800000
	v_mov_b32_e32 v223, 0xff800000
	s_branch .LBB0_666
; #define LAS __attribute__((address_space(3)))
; #define MFMA32(a, b, c) __builtin_amdgcn_mfma_f32_32x32x16_bf16((a), (b), (c), 0, 0, 0)
; __device__ __forceinline__ void mla_softmax(f32x16& s0, f32x16& s1, f32x16& o0, f32x16& o1, float& m, float& l, int k0, int qrow0, int r, int hh) {
;     ...
;     float ps = 0.f;
; #pragma unroll
;     for (int i = 0; i < 16; ++i) { s0[i] = __builtin_amdgcn_exp2f(s0[i] - m); s1[i] = __builtin_amdgcn_exp2f(s1[i] - m); ps += s0[i] + s1[i]; }
;     l = l * alpha + ps;
; __device__ __forceinline__ void mla_unit2(LAS unsigned char* lds, const bf16_t* QB, const bf16_t* KB, const bf16_t* VT, bf16_t* OB, int b, int h, int qb, int wv) {
;     ...
;             mla_softmax(sa0, sa1, oa0, oa1, ma, la, k0, q0, r, hh);
;             const LAS unsigned char* vb = cur + MK_BYTES + r * MV_ROW + hh * 16;
;             mla_softmax(sb0, sb1, ob0, ob1, mb, lb, k0, q0 + 32, r, hh);
;             bf16x8 v0 = *(const LAS bf16x8*)vb, v1 = *(const LAS bf16x8*)(vb + 32 * MV_ROW);
; #pragma unroll
;             for (int ks = 0; ks < 4; ++ks) {
;                 bf16x8 n0 = v0, n1 = v1;
;                 if (ks < 3) { n0 = *(const LAS bf16x8*)(vb + (ks + 1) * 32); n1 = *(const LAS bf16x8*)(vb + 32 * MV_ROW + (ks + 1) * 32); }
;                 const bf16x8 pa = (ks < 2) ? pack8(sa0, 8 * (ks & 1)) : pack8(sa1, 8 * (ks & 1));
;                 const bf16x8 pb = (ks < 2) ? pack8(sb0, 8 * (ks & 1)) : pack8(sb1, 8 * (ks & 1));
;                 oa0 = MFMA32(v0, pa, oa0); oa1 = MFMA32(v1, pa, oa1); ob0 = MFMA32(v0, pb, ob0); ob1 = MFMA32(v1, pb, ob1);
;                 v0 = n0; v1 = n1;
;             }
.Lmla_fastS:
	v_exp_f32_e32 v15, v128
	v_exp_f32_e32 v192, v112
	v_exp_f32_e32 v128, v129
	v_exp_f32_e32 v193, v113
	v_mov_b32_e32 v0, v130
	v_exp_f32_e32 v130, v131
	v_exp_f32_e32 v195, v115
	v_exp_f32_e32 v131, v132
	v_exp_f32_e32 v215, v116
	v_exp_f32_e32 v132, v133
	v_exp_f32_e32 v133, v117
	v_exp_f32_e32 v134, v134
	v_exp_f32_e32 v218, v118
	v_exp_f32_e32 v135, v135
	v_exp_f32_e32 v219, v119
	v_exp_f32_e32 v129, v0
	v_exp_f32_e32 v136, v136
	v_exp_f32_e32 v194, v114
	v_exp_f32_e32 v226, v120
	v_exp_f32_e32 v137, v137
	v_add_f32_e32 v112, v192, v15
	v_exp_f32_e32 v227, v121
	v_add_f32_e32 v0, 0, v112
	v_add_f32_e32 v112, v193, v128
	v_exp_f32_e32 v138, v138
	v_add_f32_e32 v0, v112, v0
	v_add_f32_e32 v112, v194, v129
	v_exp_f32_e32 v228, v122
	v_add_f32_e32 v0, v112, v0
	v_add_f32_e32 v112, v195, v130
	v_exp_f32_e32 v139, v139
	v_add_f32_e32 v0, v112, v0
	v_add_f32_e32 v112, v215, v131
	v_exp_f32_e32 v229, v123
	v_add_f32_e32 v0, v112, v0
	v_add_f32_e32 v112, v133, v132
	v_exp_f32_e32 v140, v140
	v_add_f32_e32 v0, v112, v0
	v_add_f32_e32 v112, v218, v134
	v_exp_f32_e32 v230, v124
	v_add_f32_e32 v0, v112, v0
	v_add_f32_e32 v112, v219, v135
	v_exp_f32_e32 v141, v141
	v_add_f32_e32 v0, v112, v0
	v_add_f32_e32 v112, v226, v136
	v_exp_f32_e32 v125, v125
	v_add_f32_e32 v0, v112, v0
	v_add_f32_e32 v112, v227, v137
	v_exp_f32_e32 v142, v142
	v_add_f32_e32 v0, v112, v0
	v_add_f32_e32 v112, v228, v138
	v_exp_f32_e32 v231, v126
	v_add_f32_e32 v0, v112, v0
	v_add_f32_e32 v112, v229, v139
	v_add_f32_e32 v0, v112, v0
	v_add_f32_e32 v112, v230, v140
	v_add_f32_e32 v0, v112, v0
	v_add_f32_e32 v112, v125, v141
	v_add_f32_e32 v0, v112, v0
	v_add_f32_e32 v112, v231, v142
	v_add3_u32 v234, s12, v213, v206
	v_add_f32_e32 v232, v112, v0
	ds_read_b128 v[112:115], v234 offset:13312
	v_exp_f32_e32 v233, v96
	v_mov_b32_e32 v0, v97
	v_exp_f32_e32 v235, v98
	v_mov_b32_e32 v124, v99
	ds_read_b128 v[96:99], v234 offset:17920
	ds_read_b128 v[116:119], v234 offset:13344
	v_cvt_pk_bf16_f32 v120, v15, v128
	v_mov_b32_e32 v15, v100
	v_cvt_pk_bf16_f32 v121, v129, v130
	v_cvt_pk_bf16_f32 v122, v131, v132
	v_cvt_pk_bf16_f32 v123, v134, v135
	v_exp_f32_e32 v126, v101
	v_mov_b32_e32 v100, v102
	s_waitcnt lgkmcnt(2)
	v_mfma_f32_32x32x16_bf16 v[64:79], v[112:115], v[120:123], v[64:79]
	v_exp_f32_e32 v0, v0
	v_exp_f32_e32 v124, v124
	v_exp_f32_e32 v15, v15
	ds_read_b128 v[128:131], v234 offset:17952
	v_cvt_pk_bf16_f32 v101, v235, v124
	v_cvt_pk_bf16_f32 v102, v15, v126
	s_waitcnt lgkmcnt(2)
	v_mfma_f32_32x32x16_bf16 v[48:63], v[96:99], v[120:123], v[48:63]
	v_exp_f32_e32 v121, v100
	v_exp_f32_e32 v120, v103
	v_cvt_pk_bf16_f32 v100, v233, v0
	v_exp_f32_e32 v123, v104
	v_cvt_pk_bf16_f32 v103, v121, v120
	s_nop 1
	v_mfma_f32_32x32x16_bf16 v[32:47], v[112:115], v[100:103], v[32:47]
	v_exp_f32_e32 v113, v143
	v_exp_f32_e32 v115, v127
	v_exp_f32_e32 v112, v105
	v_cvt_pk_bf16_f32 v104, v192, v193
	v_cvt_pk_bf16_f32 v105, v194, v195
	v_mfma_f32_32x32x16_bf16 v[16:31], v[96:99], v[100:103], v[16:31]
	v_exp_f32_e32 v114, v107
	v_exp_f32_e32 v134, v108
	v_exp_f32_e32 v127, v106
	v_cvt_pk_bf16_f32 v96, v136, v137
	v_cvt_pk_bf16_f32 v97, v138, v139
	v_cvt_pk_bf16_f32 v98, v140, v141
	v_cvt_pk_bf16_f32 v99, v142, v113
	v_exp_f32_e32 v122, v109
	s_waitcnt lgkmcnt(1)
	v_mfma_f32_32x32x16_bf16 v[64:79], v[116:119], v[96:99], v[64:79]
	v_exp_f32_e32 v135, v110
	ds_read_b128 v[100:103], v234 offset:13376
	v_cvt_pk_bf16_f32 v106, v215, v133
	v_cvt_pk_bf16_f32 v107, v218, v219
	s_waitcnt lgkmcnt(1)
	v_mfma_f32_32x32x16_bf16 v[48:63], v[128:131], v[96:99], v[48:63]
	v_exp_f32_e32 v132, v111
	v_cvt_pk_bf16_f32 v96, v123, v112
	v_cvt_pk_bf16_f32 v97, v127, v114
	v_cvt_pk_bf16_f32 v98, v134, v122
	v_cvt_pk_bf16_f32 v99, v135, v132
	s_waitcnt lgkmcnt(0)
	v_mfma_f32_32x32x16_bf16 v[64:79], v[100:103], v[104:107], v[64:79]
	v_mfma_f32_32x32x16_bf16 v[32:47], v[116:119], v[96:99], v[32:47]
	v_exp_f32_e32 v117, v80
	v_exp_f32_e32 v116, v81
	v_exp_f32_e32 v119, v82
	v_exp_f32_e32 v118, v83
	v_mfma_f32_32x32x16_bf16 v[16:31], v[128:131], v[96:99], v[16:31]
	ds_read_b128 v[80:83], v234 offset:17984
	ds_read_b128 v[96:99], v234 offset:13408
	v_exp_f32_e32 v129, v84
	v_exp_f32_e32 v128, v85
	ds_read_b128 v[108:111], v234 offset:18016
	v_cvt_pk_bf16_f32 v85, v119, v118
	s_waitcnt lgkmcnt(2)
	v_mfma_f32_32x32x16_bf16 v[48:63], v[80:83], v[104:107], v[48:63]
	v_exp_f32_e32 v105, v86
	v_exp_f32_e32 v104, v87
	v_cvt_pk_bf16_f32 v84, v117, v116
	v_cvt_pk_bf16_f32 v86, v129, v128
	v_add_f32_e32 v117, v117, v233
	v_cvt_pk_bf16_f32 v87, v105, v104
	v_add_f32_e32 v119, v119, v235
	v_add_f32_e32 v129, v129, v15
	v_mfma_f32_32x32x16_bf16 v[32:47], v[100:103], v[84:87], v[32:47]
	v_add_f32_e32 v100, v115, v113
	v_add_f32_e32 v100, v100, v232
	v_add_f32_e32 v100, v100, v225
	v_exp_f32_e32 v101, v88
	v_mfma_f32_32x32x16_bf16 v[16:31], v[80:83], v[84:87], v[16:31]
	v_exp_f32_e32 v85, v90
	v_cvt_pk_bf16_f32 v80, v226, v227
	v_cvt_pk_bf16_f32 v81, v228, v229
	v_cvt_pk_bf16_f32 v82, v230, v125
	v_cvt_pk_bf16_f32 v83, v231, v115
	s_waitcnt lgkmcnt(1)
	s_nop 0
	v_mfma_f32_32x32x16_bf16 v[64:79], v[96:99], v[80:83], v[64:79]
	v_exp_f32_e32 v87, v92
	v_exp_f32_e32 v14, v89
	v_exp_f32_e32 v84, v91
	v_exp_f32_e32 v86, v93
	v_exp_f32_e32 v89, v94
	v_add_f32_e32 v105, v105, v121
	s_waitcnt lgkmcnt(0)
	v_mfma_f32_32x32x16_bf16 v[48:63], v[108:111], v[80:83], v[48:63]
	v_exp_f32_e32 v88, v95
	v_cvt_pk_bf16_f32 v80, v101, v14
	v_cvt_pk_bf16_f32 v81, v85, v84
	v_cvt_pk_bf16_f32 v82, v87, v86
	v_cvt_pk_bf16_f32 v83, v89, v88
	v_add_f32_e32 v85, v85, v127
	v_add_f32_e32 v15, v101, v123
	v_mfma_f32_32x32x16_bf16 v[32:47], v[96:99], v[80:83], v[32:47]
	v_add_f32_e32 v87, v87, v134
	v_add_f32_e32 v89, v89, v135
	v_mov_b32_e32 v225, v100
	v_mfma_f32_32x32x16_bf16 v[16:31], v[108:111], v[80:83], v[16:31]
	v_add_f32_e32 v80, v116, v0
	v_add_f32_e32 v80, v80, v117
	v_add_f32_e32 v81, v118, v124
	v_add_f32_e32 v80, v80, v119
	v_add_f32_e32 v80, v80, v81
	v_add_f32_e32 v81, v128, v126
	v_add_f32_e32 v80, v80, v129
	v_add_f32_e32 v80, v80, v81
	v_add_f32_e32 v81, v104, v120
	v_add_f32_e32 v80, v80, v105
	v_add_f32_e32 v80, v80, v81
	v_add_f32_e32 v81, v14, v112
	v_add_f32_e32 v80, v80, v15
	v_add_f32_e32 v80, v80, v81
	v_add_f32_e32 v81, v84, v114
	v_add_f32_e32 v80, v80, v85
	v_add_f32_e32 v80, v80, v81
	v_add_f32_e32 v81, v86, v122
	v_add_f32_e32 v80, v80, v87
	v_add_f32_e32 v80, v80, v81
	v_add_f32_e32 v81, v88, v132
	v_add_f32_e32 v80, v80, v89
	v_add_f32_e32 v0, v80, v81
	v_add_f32_e32 v0, v0, v222
	v_mov_b32_e32 v222, v0
	s_branch .LBB0_676
